# GEMM tiles: the 128 accumulator registers are cleared with 64 v_mov_b64 instead of 128 v_mov_b32 in front of every K-loop (swiglu, proj and residual GEMM copies)
# speedup vs baseline: 1.0052x; 1.0022x over previous
; template <class Epi, class Sched, bool ALIGN_EPI = false, bool SP2 = false>
; __device__ __forceinline__ void gemm_phase(PG8_LAS unsigned char* lds, const Gemm g, const Sched& S, const Epi& E) {
;     ...
;         const char* nA = has_next ? (const char*)g.A + (size_t)nxt.pm * tstep : cA; const char* nB = has_next ? (const char*)g.Bt + (size_t)nxt.pn * tstep : cB;
;         for (int t = 0; t < nt; t += 2) {
;             const bool last = (t == nt - 2);
;             const char* a1 = cA + (size_t)(t + 1) * kstep;
;             const char* a2 = last ? nA : cA + (size_t)(t + 2) * kstep; const char* b2 = last ? nB : cB + (size_t)(t + 2) * kstep;
;     ...
; #pragma unroll
;         for (int a = 0; a < 2; ++a)
; #pragma unroll
;             for (int b = 0; b < 2; ++b)
; #pragma unroll
;                 for (int m = 0; m < 4; ++m)
; #pragma unroll
;                     for (int n = 0; n < 2; ++n) acc[a][b][m][n] = (f32x4){0.f, 0.f, 0.f, 0.f};
.LBB0_140:
	s_ashr_i32 s23, s22, 31
	s_lshl_b64 s[24:25], s[22:23], 19
	s_add_u32 s24, s92, s24
	s_addc_u32 s25, s93, s25
	s_and_b64 s[26:27], s[10:11], exec
	s_cselect_b32 s23, s25, s29
	s_cselect_b32 s46, s24, s28
	s_ashr_i32 s21, s20, 31
	s_lshl_b64 s[26:27], s[20:21], 19
	s_add_u32 s26, s7, s26
	s_addc_u32 s27, s36, s27
	s_and_b64 s[34:35], s[10:11], exec
	s_cselect_b32 s21, s27, s31
	s_cselect_b32 s47, s26, s30
	s_add_u32 s28, s28, 0x40080
	s_addc_u32 s29, s29, 0
	s_add_u32 s52, s30, 0x100
	v_mov_b64_e32 v[2:3], 0
	v_mov_b64_e32 v[4:5], 0
	v_mov_b64_e32 v[6:7], 0
	v_mov_b64_e32 v[8:9], 0
	v_mov_b64_e32 v[10:11], 0
	v_mov_b64_e32 v[12:13], 0
	v_mov_b64_e32 v[14:15], 0
	v_mov_b64_e32 v[16:17], 0
	v_mov_b64_e32 v[18:19], 0
	v_mov_b64_e32 v[20:21], 0
	v_mov_b64_e32 v[22:23], 0
	v_mov_b64_e32 v[24:25], 0
	v_mov_b64_e32 v[26:27], 0
	v_mov_b64_e32 v[28:29], 0
	v_mov_b64_e32 v[30:31], 0
	v_mov_b64_e32 v[32:33], 0
	v_mov_b64_e32 v[34:35], 0
	v_mov_b64_e32 v[36:37], 0
	v_mov_b64_e32 v[38:39], 0
	v_mov_b64_e32 v[40:41], 0
	v_mov_b64_e32 v[42:43], 0
	v_mov_b64_e32 v[44:45], 0
	v_mov_b64_e32 v[46:47], 0
	v_mov_b64_e32 v[48:49], 0
	v_mov_b64_e32 v[50:51], 0
	v_mov_b64_e32 v[52:53], 0
	v_mov_b64_e32 v[54:55], 0
	v_mov_b64_e32 v[56:57], 0
	v_mov_b64_e32 v[58:59], 0
	v_mov_b64_e32 v[60:61], 0
	v_mov_b64_e32 v[62:63], 0
	v_mov_b64_e32 v[64:65], 0
	v_mov_b64_e32 v[66:67], 0
	v_mov_b64_e32 v[68:69], 0
	v_mov_b64_e32 v[70:71], 0
	v_mov_b64_e32 v[72:73], 0
	v_mov_b64_e32 v[74:75], 0
	v_mov_b64_e32 v[76:77], 0
	v_mov_b64_e32 v[78:79], 0
	v_mov_b64_e32 v[80:81], 0
	v_mov_b64_e32 v[82:83], 0
	v_mov_b64_e32 v[84:85], 0
	v_mov_b64_e32 v[86:87], 0
	v_mov_b64_e32 v[88:89], 0
	v_mov_b64_e32 v[90:91], 0
	v_mov_b64_e32 v[92:93], 0
	v_mov_b64_e32 v[94:95], 0
	v_mov_b64_e32 v[96:97], 0
	v_mov_b64_e32 v[98:99], 0
	v_mov_b64_e32 v[100:101], 0
	v_mov_b64_e32 v[102:103], 0
	v_mov_b64_e32 v[104:105], 0
	v_mov_b64_e32 v[106:107], 0
	v_mov_b64_e32 v[108:109], 0
	v_mov_b64_e32 v[110:111], 0
	v_mov_b64_e32 v[112:113], 0
	v_mov_b64_e32 v[114:115], 0
	v_mov_b64_e32 v[116:117], 0
	v_mov_b64_e32 v[118:119], 0
	v_mov_b64_e32 v[120:121], 0
	v_mov_b64_e32 v[122:123], 0
	v_mov_b64_e32 v[124:125], 0
	v_mov_b64_e32 v[126:127], 0
	v_mov_b64_e32 v[128:129], 0
	s_addc_u32 s53, s31, 0
	s_mov_b32 s56, -2

; template <class Epi, class Sched, bool ALIGN_EPI = false, bool SP2 = false>
; __device__ __forceinline__ void gemm_phase(PG8_LAS unsigned char* lds, const Gemm g, const Sched& S, const Epi& E) {
;     ...
; #pragma unroll
;         for (int a = 0; a < 2; ++a)
; #pragma unroll
;             for (int b = 0; b < 2; ++b)
; #pragma unroll
;                 for (int m = 0; m < 4; ++m)
; #pragma unroll
;                     for (int n = 0; n < 2; ++n) acc[a][b][m][n] = (f32x4){0.f, 0.f, 0.f, 0.f};
.LBB0_634:
	s_add_u32 s12, s40, 0x80
	s_addc_u32 s13, s41, 0
	s_add_u32 s40, s38, 0x100
	v_mov_b64_e32 v[2:3], 0
	v_mov_b64_e32 v[4:5], 0
	v_mov_b64_e32 v[6:7], 0
	v_mov_b64_e32 v[8:9], 0
	v_mov_b64_e32 v[10:11], 0
	v_mov_b64_e32 v[12:13], 0
	v_mov_b64_e32 v[14:15], 0
	v_mov_b64_e32 v[16:17], 0
	v_mov_b64_e32 v[18:19], 0
	v_mov_b64_e32 v[20:21], 0
	v_mov_b64_e32 v[22:23], 0
	v_mov_b64_e32 v[24:25], 0
	v_mov_b64_e32 v[26:27], 0
	v_mov_b64_e32 v[28:29], 0
	v_mov_b64_e32 v[30:31], 0
	v_mov_b64_e32 v[32:33], 0
	v_mov_b64_e32 v[34:35], 0
	v_mov_b64_e32 v[36:37], 0
	v_mov_b64_e32 v[38:39], 0
	v_mov_b64_e32 v[40:41], 0
	v_mov_b64_e32 v[42:43], 0
	v_mov_b64_e32 v[44:45], 0
	v_mov_b64_e32 v[46:47], 0
	v_mov_b64_e32 v[48:49], 0
	v_mov_b64_e32 v[50:51], 0
	v_mov_b64_e32 v[52:53], 0
	v_mov_b64_e32 v[54:55], 0
	v_mov_b64_e32 v[56:57], 0
	v_mov_b64_e32 v[58:59], 0
	v_mov_b64_e32 v[60:61], 0
	v_mov_b64_e32 v[62:63], 0
	v_mov_b64_e32 v[64:65], 0
	v_mov_b64_e32 v[66:67], 0
	v_mov_b64_e32 v[68:69], 0
	v_mov_b64_e32 v[70:71], 0
	v_mov_b64_e32 v[72:73], 0
	v_mov_b64_e32 v[74:75], 0
	v_mov_b64_e32 v[76:77], 0
	v_mov_b64_e32 v[78:79], 0
	v_mov_b64_e32 v[80:81], 0
	v_mov_b64_e32 v[82:83], 0
	v_mov_b64_e32 v[84:85], 0
	v_mov_b64_e32 v[86:87], 0
	v_mov_b64_e32 v[88:89], 0
	v_mov_b64_e32 v[90:91], 0
	v_mov_b64_e32 v[92:93], 0
	v_mov_b64_e32 v[94:95], 0
	v_mov_b64_e32 v[96:97], 0
	v_mov_b64_e32 v[130:131], 0
	v_mov_b64_e32 v[132:133], 0
	v_mov_b64_e32 v[134:135], 0
	v_mov_b64_e32 v[136:137], 0
	v_mov_b64_e32 v[138:139], 0
	v_mov_b64_e32 v[140:141], 0
	v_mov_b64_e32 v[142:143], 0
	v_mov_b64_e32 v[144:145], 0
	v_mov_b64_e32 v[146:147], 0
	v_mov_b64_e32 v[148:149], 0
	v_mov_b64_e32 v[150:151], 0
	v_mov_b64_e32 v[152:153], 0
	v_mov_b64_e32 v[154:155], 0
	v_mov_b64_e32 v[156:157], 0
	v_mov_b64_e32 v[158:159], 0
	v_mov_b64_e32 v[160:161], 0
	s_addc_u32 s41, s39, 0
	s_mov_b32 s38, 0

; template <class Epi, class Sched, bool ALIGN_EPI = false, bool SP2 = false>
; __device__ __forceinline__ void gemm_phase(PG8_LAS unsigned char* lds, const Gemm g, const Sched& S, const Epi& E) {
;     ...
;         const char* nA = has_next ? (const char*)g.A + (size_t)nxt.pm * tstep : cA; const char* nB = has_next ? (const char*)g.Bt + (size_t)nxt.pn * tstep : cB;
;         for (int t = 0; t < nt; t += 2) {
;             const bool last = (t == nt - 2);
;             const char* a1 = cA + (size_t)(t + 1) * kstep;
;             const char* a2 = last ? nA : cA + (size_t)(t + 2) * kstep; const char* b2 = last ? nB : cB + (size_t)(t + 2) * kstep;
;     ...
; #pragma unroll
;         for (int a = 0; a < 2; ++a)
; #pragma unroll
;             for (int b = 0; b < 2; ++b)
; #pragma unroll
;                 for (int m = 0; m < 4; ++m)
; #pragma unroll
;                     for (int n = 0; n < 2; ++n) acc[a][b][m][n] = (f32x4){0.f, 0.f, 0.f, 0.f};
.LBB0_783:
	s_ashr_i32 s19, s18, 31
	s_lshl_b64 s[20:21], s[18:19], 19
	s_add_u32 s20, s92, s20
	s_addc_u32 s21, s93, s21
	s_and_b64 s[22:23], s[10:11], exec
	s_cselect_b32 s19, s21, s27
	s_cselect_b32 s33, s20, s26
	s_ashr_i32 s17, s16, 31
	s_lshl_b64 s[22:23], s[16:17], 19
	s_add_u32 s22, s1, s22
	s_addc_u32 s23, s7, s23
	s_and_b64 s[30:31], s[10:11], exec
	s_cselect_b32 s17, s23, s29
	s_cselect_b32 s44, s22, s28
	s_add_u32 s26, s26, 0x40080
	s_addc_u32 s27, s27, 0
	s_add_u32 s45, s28, 0x100
	v_mov_b64_e32 v[2:3], 0
	v_mov_b64_e32 v[4:5], 0
	v_mov_b64_e32 v[6:7], 0
	v_mov_b64_e32 v[8:9], 0
	v_mov_b64_e32 v[10:11], 0
	v_mov_b64_e32 v[12:13], 0
	v_mov_b64_e32 v[14:15], 0
	v_mov_b64_e32 v[16:17], 0
	v_mov_b64_e32 v[18:19], 0
	v_mov_b64_e32 v[20:21], 0
	v_mov_b64_e32 v[22:23], 0
	v_mov_b64_e32 v[24:25], 0
	v_mov_b64_e32 v[26:27], 0
	v_mov_b64_e32 v[28:29], 0
	v_mov_b64_e32 v[30:31], 0
	v_mov_b64_e32 v[32:33], 0
	v_mov_b64_e32 v[34:35], 0
	v_mov_b64_e32 v[36:37], 0
	v_mov_b64_e32 v[38:39], 0
	v_mov_b64_e32 v[40:41], 0
	v_mov_b64_e32 v[42:43], 0
	v_mov_b64_e32 v[44:45], 0
	v_mov_b64_e32 v[46:47], 0
	v_mov_b64_e32 v[48:49], 0
	v_mov_b64_e32 v[50:51], 0
	v_mov_b64_e32 v[52:53], 0
	v_mov_b64_e32 v[54:55], 0
	v_mov_b64_e32 v[56:57], 0
	v_mov_b64_e32 v[58:59], 0
	v_mov_b64_e32 v[60:61], 0
	v_mov_b64_e32 v[62:63], 0
	v_mov_b64_e32 v[64:65], 0
	v_mov_b64_e32 v[66:67], 0
	v_mov_b64_e32 v[68:69], 0
	v_mov_b64_e32 v[70:71], 0
	v_mov_b64_e32 v[72:73], 0
	v_mov_b64_e32 v[74:75], 0
	v_mov_b64_e32 v[76:77], 0
	v_mov_b64_e32 v[78:79], 0
	v_mov_b64_e32 v[80:81], 0
	v_mov_b64_e32 v[82:83], 0
	v_mov_b64_e32 v[84:85], 0
	v_mov_b64_e32 v[86:87], 0
	v_mov_b64_e32 v[88:89], 0
	v_mov_b64_e32 v[90:91], 0
	v_mov_b64_e32 v[92:93], 0
	v_mov_b64_e32 v[94:95], 0
	v_mov_b64_e32 v[96:97], 0
	v_mov_b64_e32 v[98:99], 0
	v_mov_b64_e32 v[100:101], 0
	v_mov_b64_e32 v[102:103], 0
	v_mov_b64_e32 v[104:105], 0
	v_mov_b64_e32 v[106:107], 0
	v_mov_b64_e32 v[108:109], 0
	v_mov_b64_e32 v[110:111], 0
	v_mov_b64_e32 v[112:113], 0
	v_mov_b64_e32 v[114:115], 0
	v_mov_b64_e32 v[116:117], 0
	v_mov_b64_e32 v[118:119], 0
	v_mov_b64_e32 v[120:121], 0
	v_mov_b64_e32 v[122:123], 0
	v_mov_b64_e32 v[124:125], 0
	v_mov_b64_e32 v[126:127], 0
	v_mov_b64_e32 v[128:129], 0
	s_addc_u32 s46, s29, 0
	s_mov_b32 s47, -2
